# MLA softmax: sub/exp pairs regrouped in batches of 4 with 4 temps (v244-247) to break the dependent sub->exp issue chain; bit-identical
# speedup vs baseline: 1.0051x; 1.0051x over previous
; #define LAS __attribute__((address_space(3)))
; __device__ __forceinline__ s16x4 vtr(const LAS unsigned char* p) { return __builtin_bit_cast(s16x4, __builtin_amdgcn_ds_read_tr16_b64_v4i16((LAS s16x4*)p)); }
; #define ATT_PACK(src, kk) do { _Pragma("unroll") for (int s2 = 0; s2 < 2; ++s2) { u32x4 w_; w_.x = cvt_pk_bf16(src[8 * s2], src[8 * s2 + 1]); w_.y = cvt_pk_bf16(src[8 * s2 + 2], src[8 * s2 + 3]); \
;             w_.z = cvt_pk_bf16(src[8 * s2 + 4], src[8 * s2 + 5]); w_.w = cvt_pk_bf16(src[8 * s2 + 6], src[8 * s2 + 7]); pf[kk][s2] = __builtin_bit_cast(bf16x8, w_); } } while (0)
; template <int MODE>
; __device__ __forceinline__ void att_smpv(f32x16 (&s)[2], f32x16 (&o)[4], float& mrun, float& lrun, float& Rrun, int tq, int tqmin, int tok0, int st, int dil, int h, int lane, const LAS unsigned char* vb) {
;     ...
;         f32x2 ps2 = (f32x2){0.f, 0.f};
; #pragma unroll
;         for (int kk = 0; kk < 2; ++kk)
; #pragma unroll
;             for (int e = 0; e < 16; e += 2) { const float p0 = __builtin_amdgcn_exp2f(s[kk][e] - mrun), p1 = __builtin_amdgcn_exp2f(s[kk][e + 1] - mrun); s[kk][e] = p0; s[kk][e + 1] = p1; ps2 += (f32x2){p0, p1}; }
;         lrun += ps2.x + ps2.y;
;         ATT_PACK(s[0], 0); ATT_PACK(s[1], 1);
;     ...
;     const int li = lane & 15, tq_ = li >> 2, tp = li & 3;
;     const unsigned base0 = (unsigned)((4 * h + tq_) * 256 + (tq_ << 6) + (2 * ((lane >> 4) & 1) + (tp >> 1)) * 16 + 8 * (tp & 1));
; #pragma unroll
;     for (int b = 0; b < 4; ++b)
; #pragma unroll
;         for (int kk = 0; kk < 2; ++kk)
; #pragma unroll
;             for (int s2 = 0; s2 < 2; ++s2) { const LAS unsigned char* p = vb + ((base0 ^ (unsigned)(b << 6)) + (unsigned)((32 * kk + 16 * s2) * 256));
;                 const s16x4 lo = vtr(p), hi = vtr(p + 8 * 256);
;                 const bf16x8 vf = (bf16x8){lo[0], lo[1], lo[2], lo[3], hi[0], hi[1], hi[2], hi[3]};
;                 o[b] = __builtin_amdgcn_mfma_f32_32x32x16_bf16(vf, pf[kk][s2], o[b], 0, 0, 0); }
.LBB0_249:
	v_sub_f32_e32 v244, v82, v145
	v_sub_f32_e32 v245, v83, v145
	v_sub_f32_e32 v246, v84, v145
	v_sub_f32_e32 v247, v85, v145
	v_exp_f32_e32 v82, v244
	v_exp_f32_e32 v83, v245
	v_exp_f32_e32 v84, v246
	v_exp_f32_e32 v85, v247
	v_sub_f32_e32 v244, v86, v145
	v_sub_f32_e32 v245, v87, v145
	v_sub_f32_e32 v246, v88, v145
	v_sub_f32_e32 v247, v89, v145
	v_exp_f32_e32 v86, v244
	v_exp_f32_e32 v87, v245
	v_exp_f32_e32 v88, v246
	v_exp_f32_e32 v89, v247
	v_sub_f32_e32 v244, v90, v145
	v_sub_f32_e32 v245, v91, v145
	v_sub_f32_e32 v246, v92, v145
	v_sub_f32_e32 v247, v93, v145
	v_exp_f32_e32 v90, v244
	v_exp_f32_e32 v91, v245
	v_exp_f32_e32 v92, v246
	v_exp_f32_e32 v93, v247
	v_sub_f32_e32 v244, v94, v145
	v_sub_f32_e32 v245, v95, v145
	v_sub_f32_e32 v246, v96, v145
	v_exp_f32_e32 v94, v244
	v_exp_f32_e32 v95, v245
	v_exp_f32_e32 v96, v246
	v_sub_f32_e32 v0, v97, v145
	v_pk_add_f32 v[146:147], v[82:83], 0 op_sel_hi:[1,0]
	v_exp_f32_e32 v97, v0
	v_sub_f32_e32 v0, v66, v145
	v_pk_add_f32 v[146:147], v[84:85], v[146:147]
	v_exp_f32_e32 v66, v0
	v_sub_f32_e32 v0, v67, v145
	v_pk_add_f32 v[146:147], v[86:87], v[146:147]
	v_exp_f32_e32 v67, v0
	v_sub_f32_e32 v0, v68, v145
	v_pk_add_f32 v[146:147], v[88:89], v[146:147]
	v_exp_f32_e32 v68, v0
	v_sub_f32_e32 v0, v69, v145
	v_pk_add_f32 v[146:147], v[90:91], v[146:147]
	v_exp_f32_e32 v69, v0
	v_sub_f32_e32 v0, v70, v145
	v_pk_add_f32 v[146:147], v[92:93], v[146:147]
	v_exp_f32_e32 v148, v0
	v_sub_f32_e32 v0, v71, v145
	v_pk_add_f32 v[146:147], v[94:95], v[146:147]
	v_exp_f32_e32 v149, v0
	v_pk_add_f32 v[146:147], v[96:97], v[146:147]
	v_sub_f32_e32 v0, v72, v145
	v_pk_add_f32 v[146:147], v[66:67], v[146:147]
	s_nop 0
	v_pk_add_f32 v[146:147], v[68:69], v[146:147]
	s_nop 0
	v_pk_add_f32 v[70:71], v[148:149], v[146:147]
	v_exp_f32_e32 v146, v0
	v_sub_f32_e32 v244, v73, v145
	v_sub_f32_e32 v245, v74, v145
	v_sub_f32_e32 v246, v75, v145
	v_sub_f32_e32 v247, v76, v145
	v_exp_f32_e32 v147, v244
	v_exp_f32_e32 v150, v245
	v_exp_f32_e32 v151, v246
	v_exp_f32_e32 v152, v247
	v_sub_f32_e32 v244, v77, v145
	v_sub_f32_e32 v245, v78, v145
	v_sub_f32_e32 v246, v79, v145
	v_sub_f32_e32 v247, v80, v145
	v_exp_f32_e32 v153, v244
	v_exp_f32_e32 v166, v245
	v_exp_f32_e32 v167, v246
	v_exp_f32_e32 v168, v247
	v_sub_f32_e32 v0, v81, v145
	v_pk_add_f32 v[70:71], v[146:147], v[70:71]
	v_exp_f32_e32 v169, v0
	v_pk_add_f32 v[70:71], v[150:151], v[70:71]
	s_nop 0
	v_pk_add_f32 v[70:71], v[152:153], v[70:71]
	s_nop 0
	v_pk_add_f32 v[70:71], v[166:167], v[70:71]
	s_nop 0
	v_pk_add_f32 v[70:71], v[168:169], v[70:71]
	s_nop 0
	v_add_f32_e32 v0, v70, v71
	v_add_f32_e32 v144, v144, v0
	v_add_u32_e32 v0, s4, v135
	v_cvt_pk_bf16_f32 v70, v82, v83
	v_cvt_pk_bf16_f32 v71, v84, v85
	v_cvt_pk_bf16_f32 v72, v86, v87
	v_cvt_pk_bf16_f32 v73, v88, v89
	v_cvt_pk_bf16_f32 v74, v90, v91
	v_cvt_pk_bf16_f32 v75, v92, v93
	v_cvt_pk_bf16_f32 v76, v94, v95
	v_cvt_pk_bf16_f32 v77, v96, v97
	v_cvt_pk_bf16_f32 v78, v66, v67
	v_cvt_pk_bf16_f32 v79, v68, v69
	v_cvt_pk_bf16_f32 v80, v148, v149
	v_cvt_pk_bf16_f32 v81, v146, v147
	v_cvt_pk_bf16_f32 v66, v150, v151
	v_cvt_pk_bf16_f32 v67, v152, v153
	v_cvt_pk_bf16_f32 v68, v166, v167
	v_cvt_pk_bf16_f32 v69, v168, v169
	s_waitcnt vmcnt(0)
	ds_read_b64_tr_b16 v[228:229], v0 offset:49152
	ds_read_b64_tr_b16 v[230:231], v0 offset:51200
	ds_read_b64_tr_b16 v[232:233], v0 offset:53248
	ds_read_b64_tr_b16 v[234:235], v0 offset:55296
	ds_read_b64_tr_b16 v[236:237], v0 offset:57344
	ds_read_b64_tr_b16 v[238:239], v0 offset:59392
	ds_read_b64_tr_b16 v[240:241], v0 offset:61440
	ds_read_b64_tr_b16 v[242:243], v0 offset:63488
	s_waitcnt lgkmcnt(6)
	v_mfma_f32_32x32x16_bf16 v[50:65], v[228:231], v[70:73], v[50:65]
	v_add_u32_e32 v0, s4, v136
	ds_read_b64_tr_b16 v[228:229], v0 offset:49152
	ds_read_b64_tr_b16 v[230:231], v0 offset:51200
	s_waitcnt lgkmcnt(6)
	v_mfma_f32_32x32x16_bf16 v[50:65], v[232:235], v[74:77], v[50:65]
	ds_read_b64_tr_b16 v[232:233], v0 offset:53248
	ds_read_b64_tr_b16 v[234:235], v0 offset:55296
	s_waitcnt lgkmcnt(6)
	v_mfma_f32_32x32x16_bf16 v[50:65], v[236:239], v[78:81], v[50:65]
	ds_read_b64_tr_b16 v[236:237], v0 offset:57344
	ds_read_b64_tr_b16 v[238:239], v0 offset:59392
	s_waitcnt lgkmcnt(6)
	v_mfma_f32_32x32x16_bf16 v[50:65], v[240:243], v[66:69], v[50:65]
	ds_read_b64_tr_b16 v[240:241], v0 offset:61440
	ds_read_b64_tr_b16 v[242:243], v0 offset:63488
	s_waitcnt lgkmcnt(6)
	v_mfma_f32_32x32x16_bf16 v[34:49], v[228:231], v[70:73], v[34:49]
	v_add_u32_e32 v0, s4, v137
	ds_read_b64_tr_b16 v[228:229], v0 offset:49152
	ds_read_b64_tr_b16 v[230:231], v0 offset:51200
	s_waitcnt lgkmcnt(6)
	v_mfma_f32_32x32x16_bf16 v[34:49], v[232:235], v[74:77], v[34:49]
	ds_read_b64_tr_b16 v[232:233], v0 offset:53248
	ds_read_b64_tr_b16 v[234:235], v0 offset:55296
	s_waitcnt lgkmcnt(6)
	v_mfma_f32_32x32x16_bf16 v[34:49], v[236:239], v[78:81], v[34:49]
	ds_read_b64_tr_b16 v[236:237], v0 offset:57344
	ds_read_b64_tr_b16 v[238:239], v0 offset:59392
	s_waitcnt lgkmcnt(6)
	v_mfma_f32_32x32x16_bf16 v[34:49], v[240:243], v[66:69], v[34:49]
	ds_read_b64_tr_b16 v[240:241], v0 offset:61440
	ds_read_b64_tr_b16 v[242:243], v0 offset:63488
	s_waitcnt lgkmcnt(6)
	v_mfma_f32_32x32x16_bf16 v[18:33], v[228:231], v[70:73], v[18:33]
	v_add_u32_e32 v0, s4, v138
	ds_read_b64_tr_b16 v[228:229], v0 offset:49152
	ds_read_b64_tr_b16 v[230:231], v0 offset:51200
	s_waitcnt lgkmcnt(6)
	v_mfma_f32_32x32x16_bf16 v[18:33], v[232:235], v[74:77], v[18:33]
	ds_read_b64_tr_b16 v[232:233], v0 offset:53248
	ds_read_b64_tr_b16 v[234:235], v0 offset:55296
	s_waitcnt lgkmcnt(6)
	v_mfma_f32_32x32x16_bf16 v[18:33], v[236:239], v[78:81], v[18:33]
	ds_read_b64_tr_b16 v[236:237], v0 offset:57344
	ds_read_b64_tr_b16 v[238:239], v0 offset:59392
	s_waitcnt lgkmcnt(6)
	v_mfma_f32_32x32x16_bf16 v[18:33], v[240:243], v[66:69], v[18:33]
	ds_read_b64_tr_b16 v[240:241], v0 offset:61440
	ds_read_b64_tr_b16 v[242:243], v0 offset:63488
	s_waitcnt lgkmcnt(6)
	v_mfma_f32_32x32x16_bf16 v[2:17], v[228:231], v[70:73], v[2:17]
	s_waitcnt lgkmcnt(4)
	v_mfma_f32_32x32x16_bf16 v[2:17], v[232:235], v[74:77], v[2:17]
	s_waitcnt lgkmcnt(2)
	v_mfma_f32_32x32x16_bf16 v[2:17], v[236:239], v[78:81], v[2:17]
	s_waitcnt lgkmcnt(0)
	v_mfma_f32_32x32x16_bf16 v[2:17], v[240:243], v[66:69], v[2:17]

; #define LAS __attribute__((address_space(3)))
; __device__ __forceinline__ s16x4 vtr(const LAS unsigned char* p) { return __builtin_bit_cast(s16x4, __builtin_amdgcn_ds_read_tr16_b64_v4i16((LAS s16x4*)p)); }
; #define ATT_PACK(src, kk) do { _Pragma("unroll") for (int s2 = 0; s2 < 2; ++s2) { u32x4 w_; w_.x = cvt_pk_bf16(src[8 * s2], src[8 * s2 + 1]); w_.y = cvt_pk_bf16(src[8 * s2 + 2], src[8 * s2 + 3]); \
;             w_.z = cvt_pk_bf16(src[8 * s2 + 4], src[8 * s2 + 5]); w_.w = cvt_pk_bf16(src[8 * s2 + 6], src[8 * s2 + 7]); pf[kk][s2] = __builtin_bit_cast(bf16x8, w_); } } while (0)
; template <int MODE>
; __device__ __forceinline__ void att_smpv(f32x16 (&s)[2], f32x16 (&o)[4], float& mrun, float& lrun, float& Rrun, int tq, int tqmin, int tok0, int st, int dil, int h, int lane, const LAS unsigned char* vb) {
;     ...
;         f32x2 ps2 = (f32x2){0.f, 0.f};
; #pragma unroll
;         for (int kk = 0; kk < 2; ++kk)
; #pragma unroll
;             for (int e = 0; e < 16; e += 2) { const float p0 = __builtin_amdgcn_exp2f(s[kk][e] - mrun), p1 = __builtin_amdgcn_exp2f(s[kk][e + 1] - mrun); s[kk][e] = p0; s[kk][e + 1] = p1; ps2 += (f32x2){p0, p1}; }
;         lrun += ps2.x + ps2.y;
;         ATT_PACK(s[0], 0); ATT_PACK(s[1], 1);
;     ...
;     const int li = lane & 15, tq_ = li >> 2, tp = li & 3;
;     const unsigned base0 = (unsigned)((4 * h + tq_) * 256 + (tq_ << 6) + (2 * ((lane >> 4) & 1) + (tp >> 1)) * 16 + 8 * (tp & 1));
; #pragma unroll
;     for (int b = 0; b < 4; ++b)
; #pragma unroll
;         for (int kk = 0; kk < 2; ++kk)
; #pragma unroll
;             for (int s2 = 0; s2 < 2; ++s2) { const LAS unsigned char* p = vb + ((base0 ^ (unsigned)(b << 6)) + (unsigned)((32 * kk + 16 * s2) * 256));
;                 const s16x4 lo = vtr(p), hi = vtr(p + 8 * 256);
;                 const bf16x8 vf = (bf16x8){lo[0], lo[1], lo[2], lo[3], hi[0], hi[1], hi[2], hi[3]};
;                 o[b] = __builtin_amdgcn_mfma_f32_32x32x16_bf16(vf, pf[kk][s2], o[b], 0, 0, 0); }
; template <int DK, int MODE>
; __device__ __forceinline__ void attn_unit(LAS unsigned char* lds, const bf16_t* Q, int ldq, const bf16_t* Kp, int ldk, const bf16_t* Vp, int ldv, bf16_t* O, int ldo, int u0, int r4) {
;     ...
;     for (int p = 0; p < npairs; ++p) {
;         if (p + 1 < npairs) ATT_DMAPAIR(p + 1);
.LBB0_267:
	v_sub_f32_e32 v244, v82, v145
	v_sub_f32_e32 v245, v83, v145
	v_sub_f32_e32 v246, v84, v145
	v_sub_f32_e32 v247, v85, v145
	v_exp_f32_e32 v82, v244
	v_exp_f32_e32 v83, v245
	v_exp_f32_e32 v84, v246
	v_exp_f32_e32 v85, v247
	v_sub_f32_e32 v244, v86, v145
	v_sub_f32_e32 v245, v87, v145
	v_sub_f32_e32 v246, v88, v145
	v_sub_f32_e32 v247, v89, v145
	v_exp_f32_e32 v86, v244
	v_exp_f32_e32 v87, v245
	v_exp_f32_e32 v88, v246
	v_exp_f32_e32 v89, v247
	v_sub_f32_e32 v244, v90, v145
	v_sub_f32_e32 v245, v91, v145
	v_sub_f32_e32 v246, v92, v145
	v_sub_f32_e32 v247, v93, v145
	v_exp_f32_e32 v90, v244
	v_exp_f32_e32 v91, v245
	v_exp_f32_e32 v92, v246
	v_exp_f32_e32 v93, v247
	v_sub_f32_e32 v244, v94, v145
	v_sub_f32_e32 v245, v95, v145
	v_sub_f32_e32 v246, v96, v145
	v_exp_f32_e32 v94, v244
	v_exp_f32_e32 v95, v245
	v_exp_f32_e32 v96, v246
	v_sub_f32_e32 v0, v97, v145
	v_pk_add_f32 v[146:147], v[82:83], 0 op_sel_hi:[1,0]
	v_exp_f32_e32 v97, v0
	v_sub_f32_e32 v0, v66, v145
	v_pk_add_f32 v[146:147], v[84:85], v[146:147]
	v_exp_f32_e32 v66, v0
	v_sub_f32_e32 v0, v67, v145
	v_pk_add_f32 v[146:147], v[86:87], v[146:147]
	v_exp_f32_e32 v67, v0
	v_sub_f32_e32 v0, v68, v145
	v_pk_add_f32 v[146:147], v[88:89], v[146:147]
	v_exp_f32_e32 v68, v0
	v_sub_f32_e32 v0, v69, v145
	v_pk_add_f32 v[146:147], v[90:91], v[146:147]
	v_exp_f32_e32 v69, v0
	v_sub_f32_e32 v0, v70, v145
	v_pk_add_f32 v[146:147], v[92:93], v[146:147]
	v_exp_f32_e32 v148, v0
	v_sub_f32_e32 v0, v71, v145
	v_pk_add_f32 v[146:147], v[94:95], v[146:147]
	v_exp_f32_e32 v149, v0
	v_pk_add_f32 v[146:147], v[96:97], v[146:147]
	v_sub_f32_e32 v0, v72, v145
	v_pk_add_f32 v[146:147], v[66:67], v[146:147]
	s_nop 0
	v_pk_add_f32 v[146:147], v[68:69], v[146:147]
	s_nop 0
	v_pk_add_f32 v[70:71], v[148:149], v[146:147]
	v_exp_f32_e32 v146, v0
	v_sub_f32_e32 v244, v73, v145
	v_sub_f32_e32 v245, v74, v145
	v_sub_f32_e32 v246, v75, v145
	v_sub_f32_e32 v247, v76, v145
	v_exp_f32_e32 v147, v244
	v_exp_f32_e32 v150, v245
	v_exp_f32_e32 v151, v246
	v_exp_f32_e32 v152, v247
	v_sub_f32_e32 v244, v77, v145
	v_sub_f32_e32 v245, v78, v145
	v_sub_f32_e32 v246, v79, v145
	v_sub_f32_e32 v247, v80, v145
	v_exp_f32_e32 v153, v244
	v_exp_f32_e32 v166, v245
	v_exp_f32_e32 v167, v246
	v_exp_f32_e32 v168, v247
	v_sub_f32_e32 v0, v81, v145
	v_pk_add_f32 v[70:71], v[146:147], v[70:71]
	v_exp_f32_e32 v169, v0
	v_pk_add_f32 v[70:71], v[150:151], v[70:71]
	s_nop 0
	v_pk_add_f32 v[70:71], v[152:153], v[70:71]
	s_nop 0
	v_pk_add_f32 v[70:71], v[166:167], v[70:71]
	s_nop 0
	v_pk_add_f32 v[70:71], v[168:169], v[70:71]
	s_nop 0
	v_add_f32_e32 v0, v70, v71
	v_add_f32_e32 v144, v144, v0
	v_add_u32_e32 v0, s5, v135
	v_cvt_pk_bf16_f32 v70, v82, v83
	v_cvt_pk_bf16_f32 v71, v84, v85
	v_cvt_pk_bf16_f32 v72, v86, v87
	v_cvt_pk_bf16_f32 v73, v88, v89
	v_cvt_pk_bf16_f32 v74, v90, v91
	v_cvt_pk_bf16_f32 v75, v92, v93
	v_cvt_pk_bf16_f32 v76, v94, v95
	v_cvt_pk_bf16_f32 v77, v96, v97
	v_cvt_pk_bf16_f32 v78, v66, v67
	v_cvt_pk_bf16_f32 v79, v68, v69
	v_cvt_pk_bf16_f32 v80, v148, v149
	v_cvt_pk_bf16_f32 v81, v146, v147
	v_cvt_pk_bf16_f32 v66, v150, v151
	v_cvt_pk_bf16_f32 v67, v152, v153
	v_cvt_pk_bf16_f32 v68, v166, v167
	v_cvt_pk_bf16_f32 v69, v168, v169
	s_waitcnt vmcnt(0)
	ds_read_b64_tr_b16 v[228:229], v0 offset:16384
	ds_read_b64_tr_b16 v[230:231], v0 offset:18432
	ds_read_b64_tr_b16 v[232:233], v0 offset:20480
	ds_read_b64_tr_b16 v[234:235], v0 offset:22528
	ds_read_b64_tr_b16 v[236:237], v0 offset:24576
	ds_read_b64_tr_b16 v[238:239], v0 offset:26624
	ds_read_b64_tr_b16 v[240:241], v0 offset:28672
	ds_read_b64_tr_b16 v[242:243], v0 offset:30720
	s_waitcnt lgkmcnt(6)
	v_mfma_f32_32x32x16_bf16 v[50:65], v[228:231], v[70:73], v[50:65]
	v_add_u32_e32 v0, s5, v136
	ds_read_b64_tr_b16 v[228:229], v0 offset:16384
	ds_read_b64_tr_b16 v[230:231], v0 offset:18432
	s_waitcnt lgkmcnt(6)
	v_mfma_f32_32x32x16_bf16 v[50:65], v[232:235], v[74:77], v[50:65]
	ds_read_b64_tr_b16 v[232:233], v0 offset:20480
	ds_read_b64_tr_b16 v[234:235], v0 offset:22528
	s_waitcnt lgkmcnt(6)
	v_mfma_f32_32x32x16_bf16 v[50:65], v[236:239], v[78:81], v[50:65]
	ds_read_b64_tr_b16 v[236:237], v0 offset:24576
	ds_read_b64_tr_b16 v[238:239], v0 offset:26624
	s_waitcnt lgkmcnt(6)
	v_mfma_f32_32x32x16_bf16 v[50:65], v[240:243], v[66:69], v[50:65]
	ds_read_b64_tr_b16 v[240:241], v0 offset:28672
	ds_read_b64_tr_b16 v[242:243], v0 offset:30720
	s_waitcnt lgkmcnt(6)
	v_mfma_f32_32x32x16_bf16 v[34:49], v[228:231], v[70:73], v[34:49]
	v_add_u32_e32 v0, s5, v137
	ds_read_b64_tr_b16 v[228:229], v0 offset:16384
	ds_read_b64_tr_b16 v[230:231], v0 offset:18432
	s_waitcnt lgkmcnt(6)
	v_mfma_f32_32x32x16_bf16 v[34:49], v[232:235], v[74:77], v[34:49]
	ds_read_b64_tr_b16 v[232:233], v0 offset:20480
	ds_read_b64_tr_b16 v[234:235], v0 offset:22528
	s_waitcnt lgkmcnt(6)
	v_mfma_f32_32x32x16_bf16 v[34:49], v[236:239], v[78:81], v[34:49]
	ds_read_b64_tr_b16 v[236:237], v0 offset:24576
	ds_read_b64_tr_b16 v[238:239], v0 offset:26624
	s_waitcnt lgkmcnt(6)
	v_mfma_f32_32x32x16_bf16 v[34:49], v[240:243], v[66:69], v[34:49]
	ds_read_b64_tr_b16 v[240:241], v0 offset:28672
	ds_read_b64_tr_b16 v[242:243], v0 offset:30720
	s_waitcnt lgkmcnt(6)
	v_mfma_f32_32x32x16_bf16 v[18:33], v[228:231], v[70:73], v[18:33]
	v_add_u32_e32 v0, s5, v138
	ds_read_b64_tr_b16 v[228:229], v0 offset:16384
	ds_read_b64_tr_b16 v[230:231], v0 offset:18432
	s_waitcnt lgkmcnt(6)
	v_mfma_f32_32x32x16_bf16 v[18:33], v[232:235], v[74:77], v[18:33]
	ds_read_b64_tr_b16 v[232:233], v0 offset:20480
	ds_read_b64_tr_b16 v[234:235], v0 offset:22528
	s_waitcnt lgkmcnt(6)
	v_mfma_f32_32x32x16_bf16 v[18:33], v[236:239], v[78:81], v[18:33]
	ds_read_b64_tr_b16 v[236:237], v0 offset:24576
	ds_read_b64_tr_b16 v[238:239], v0 offset:26624
	s_waitcnt lgkmcnt(6)
	v_mfma_f32_32x32x16_bf16 v[18:33], v[240:243], v[66:69], v[18:33]
	ds_read_b64_tr_b16 v[240:241], v0 offset:28672
	ds_read_b64_tr_b16 v[242:243], v0 offset:30720
	s_waitcnt lgkmcnt(6)
	v_mfma_f32_32x32x16_bf16 v[2:17], v[228:231], v[70:73], v[2:17]
	s_waitcnt lgkmcnt(4)
	v_mfma_f32_32x32x16_bf16 v[2:17], v[232:235], v[74:77], v[2:17]
	s_waitcnt lgkmcnt(2)
	v_mfma_f32_32x32x16_bf16 v[2:17], v[236:239], v[78:81], v[2:17]
	s_waitcnt lgkmcnt(0)
	v_mfma_f32_32x32x16_bf16 v[2:17], v[240:243], v[66:69], v[2:17]
	s_add_i32 s5, s37, 1
	s_cmp_gt_i32 s5, s21
	s_cbranch_scc1 .LBB0_250
